# P1 norm: batch-aligned rows (parameters stay in registers) plus one-row-ahead x prefetch with counted vmcnt
# speedup vs baseline: 1.0155x; 1.0155x over previous
.LBB0_83:
	s_or_b64 exec, exec, s[10:11]
	v_lshl_add_u64 v[2:3], v[2:3], 0, v[50:51]
	v_readfirstlane_b32 s32, v34
	v_readlane_b32 s98, v250, 21
	v_readlane_b32 s99, v250, 22
	v_lshlrev_b64 v[72:73], 12, v[72:73]
	s_nop 1
	s_add_i32 s35, s32, 0x100
	s_lshr_b32 s78, s32, 11
	s_lshl_b32 s78, s78, 8
	s_and_b32 s81, s32, 0xff
	s_or_b32 s78, s78, s81
	s_add_i32 s78, s78, 0x4000
	s_and_b32 s41, s32, 0x700
	s_cmp_eq_u32 s41, 0x700
	s_cselect_b32 s35, s78, s35
	s_cmp_ge_u32 s32, 0x4000
	s_cselect_b32 s35, 0x4800, s35
	s_cmp_ge_u32 s32, 0x4000
	s_cbranch_scc1 .Lnorm_ctx
	s_and_b32 s41, s32, 0x700
	s_cmp_eq_u32 s41, 0
	s_cbranch_scc1 .Lnorm_first
	s_lshl_b32 s83, s35, 13
	s_add_u32 s100, s98, s83
	s_addc_u32 s101, s99, 0
	s_sub_i32 s83, s35, 0x4000
	s_lshl_b32 s83, s83, 13
	s_add_u32 s86, s48, s83
	s_addc_u32 s87, s49, 0
	s_cmp_lt_u32 s35, 0x4000
	s_cselect_b32 s100, s100, s86
	s_cselect_b32 s101, s101, s87
	v_lshl_add_u64 v[92:93], v[46:47], 0, v[72:73]
	s_waitcnt vmcnt(8)
	v_mov_b64_e32 v[30:31], v[206:207]
	v_mov_b64_e32 v[32:33], v[208:209]
	v_mov_b64_e32 v[26:27], v[210:211]
	v_mov_b64_e32 v[28:29], v[212:213]
	v_mov_b64_e32 v[22:23], v[214:215]
	v_mov_b64_e32 v[24:25], v[216:217]
	v_mov_b64_e32 v[18:19], v[218:219]
	v_mov_b64_e32 v[20:21], v[220:221]
	v_mov_b64_e32 v[14:15], v[222:223]
	v_mov_b64_e32 v[16:17], v[224:225]
	v_mov_b64_e32 v[6:7], v[226:227]
	v_mov_b64_e32 v[8:9], v[228:229]
	v_mov_b64_e32 v[82:83], v[242:243]
	v_mov_b64_e32 v[84:85], v[244:245]
	v_mov_b64_e32 v[86:87], v[246:247]
	v_mov_b64_e32 v[88:89], v[248:249]
	global_load_dwordx4 v[206:209], v50, s[100:101]
	global_load_dwordx4 v[210:213], v50, s[100:101] offset:1024
	global_load_dwordx4 v[214:217], v50, s[100:101] offset:2048
	global_load_dwordx4 v[218:221], v50, s[100:101] offset:3072
	global_load_dwordx4 v[222:225], v58, s[100:101]
	global_load_dwordx4 v[226:229], v58, s[100:101] offset:1024
	global_load_dwordx4 v[242:245], v58, s[100:101] offset:2048
	global_load_dwordx4 v[246:249], v58, s[100:101] offset:3072
	v_mov_b32_e32 v34, s35
	v_mov_b32_e32 v35, 0
	v_cmp_lt_i32_e32 vcc, s12, v34
	s_or_b64 s[8:9], vcc, s[8:9]
	v_mul_f32_e32 v4, v31, v31
	v_mul_f32_e32 v5, v27, v27
	v_fmac_f32_e32 v4, v30, v30
	v_fmac_f32_e32 v5, v26, v26
	v_fmac_f32_e32 v4, v32, v32
	v_fmac_f32_e32 v5, v28, v28
	v_fmac_f32_e32 v4, v33, v33
	v_fmac_f32_e32 v5, v29, v29
	v_add_f32_e32 v4, v4, v5
	v_mul_f32_e32 v5, v23, v23
	v_fmac_f32_e32 v5, v22, v22
	v_fmac_f32_e32 v5, v24, v24
	v_fmac_f32_e32 v5, v25, v25
	v_add_f32_e32 v4, v4, v5
	v_mul_f32_e32 v5, v19, v19
	v_fmac_f32_e32 v5, v18, v18
	v_fmac_f32_e32 v5, v20, v20
	v_fmac_f32_e32 v5, v21, v21
	v_mov_b32_e32 v10, v15
	v_mov_b32_e32 v11, v7
	v_add_f32_e32 v12, v4, v5
	v_mov_b32_e32 v4, v14
	v_mov_b32_e32 v5, v6
	v_pk_mul_f32 v[10:11], v[10:11], v[10:11]
	s_nop 0
	v_pk_fma_f32 v[4:5], v[4:5], v[4:5], v[10:11]
	v_mov_b32_e32 v10, v16
	v_mov_b32_e32 v11, v8
	v_pk_fma_f32 v[4:5], v[10:11], v[10:11], v[4:5]
	v_mov_b32_e32 v10, v17
	v_mov_b32_e32 v11, v9
	v_pk_fma_f32 v[4:5], v[10:11], v[10:11], v[4:5]
	s_nop 0
	v_add_f32_e32 v4, v12, v4
	v_add_f32_e32 v66, v4, v5
	v_mov_b32_e32 v74, v83
	v_mov_b32_e32 v75, v87
	v_mov_b32_e32 v70, v82
	v_mov_b32_e32 v71, v86
	v_pk_mul_f32 v[74:75], v[74:75], v[74:75]
	s_nop 0
	v_pk_fma_f32 v[70:71], v[70:71], v[70:71], v[74:75]
	v_mov_b32_e32 v74, v84
	v_mov_b32_e32 v75, v88
	v_pk_fma_f32 v[70:71], v[74:75], v[74:75], v[70:71]
	v_mov_b32_e32 v74, v85
	v_mov_b32_e32 v75, v89
	v_pk_fma_f32 v[70:71], v[74:75], v[74:75], v[70:71]
	s_nop 0
	v_add_f32_e32 v66, v66, v70
	v_add_f32_e32 v66, v66, v71
	ds_bpermute_b32 v70, v67, v66
	s_waitcnt lgkmcnt(0)
	v_add_f32_e32 v66, v66, v70
	ds_bpermute_b32 v70, v76, v66
	s_waitcnt lgkmcnt(0)
	v_add_f32_e32 v66, v66, v70
	ds_bpermute_b32 v70, v77, v66
	s_waitcnt lgkmcnt(0)
	v_add_f32_e32 v66, v66, v70
	ds_bpermute_b32 v70, v78, v66
	s_waitcnt lgkmcnt(0)
	v_add_f32_e32 v66, v66, v70
	ds_bpermute_b32 v70, v79, v66
	s_waitcnt lgkmcnt(0)
	v_add_f32_e32 v66, v66, v70
	ds_bpermute_b32 v70, v80, v66
	s_waitcnt lgkmcnt(0)
	v_add_f32_e32 v66, v66, v70
	v_fmamk_f32 v66, v66, 0x3a000000, v230
	v_cmp_gt_f32_e32 vcc, s70, v66
	v_mul_f32_e32 v70, 0x4b800000, v66
	s_nop 0
	v_cndmask_b32_e32 v66, v66, v70, vcc
	v_rsq_f32_e32 v66, v66
	s_nop 0
	v_mul_f32_e32 v70, 0x45800000, v66
	v_cndmask_b32_e32 v66, v66, v70, vcc
	v_pk_mul_f32 v[30:31], v[30:31], v[66:67] op_sel_hi:[1,0]
	v_pk_mul_f32 v[32:33], v[32:33], v[66:67] op_sel_hi:[1,0]
	v_pk_mul_f32 v[26:27], v[26:27], v[66:67] op_sel_hi:[1,0]
	v_pk_mul_f32 v[28:29], v[28:29], v[66:67] op_sel_hi:[1,0]
	v_pk_mul_f32 v[22:23], v[22:23], v[66:67] op_sel_hi:[1,0]
	v_pk_mul_f32 v[24:25], v[24:25], v[66:67] op_sel_hi:[1,0]
	v_pk_mul_f32 v[18:19], v[18:19], v[66:67] op_sel_hi:[1,0]
	v_pk_mul_f32 v[20:21], v[20:21], v[66:67] op_sel_hi:[1,0]
	v_pk_mul_f32 v[14:15], v[14:15], v[66:67] op_sel_hi:[1,0]
	v_pk_mul_f32 v[16:17], v[16:17], v[66:67] op_sel_hi:[1,0]
	v_pk_mul_f32 v[6:7], v[6:7], v[66:67] op_sel_hi:[1,0]
	v_pk_mul_f32 v[8:9], v[8:9], v[66:67] op_sel_hi:[1,0]
	v_pk_mul_f32 v[82:83], v[82:83], v[66:67] op_sel_hi:[1,0]
	v_pk_mul_f32 v[84:85], v[84:85], v[66:67] op_sel_hi:[1,0]
	v_pk_mul_f32 v[86:87], v[86:87], v[66:67] op_sel_hi:[1,0]
	v_pk_mul_f32 v[88:89], v[88:89], v[66:67] op_sel_hi:[1,0]
	v_pk_mul_f32 v[30:31], v[94:95], v[30:31]
	v_pk_mul_f32 v[32:33], v[96:97], v[32:33]
	v_pk_add_f32 v[4:5], v[158:159], 1.0 op_sel_hi:[1,0]
	v_pk_add_f32 v[10:11], v[160:161], 1.0 op_sel_hi:[1,0]
	v_pk_fma_f32 v[30:31], v[4:5], v[30:31], v[126:127]
	v_pk_fma_f32 v[32:33], v[10:11], v[32:33], v[128:129]
	v_cvt_pk_bf16_f32 v12, v30, v31
	v_cvt_pk_bf16_f32 v13, v32, v33
	global_store_dwordx2 v[92:93], v[12:13], off
	v_pk_mul_f32 v[26:27], v[98:99], v[26:27]
	v_pk_mul_f32 v[28:29], v[100:101], v[28:29]
	v_pk_add_f32 v[4:5], v[162:163], 1.0 op_sel_hi:[1,0]
	v_pk_add_f32 v[10:11], v[164:165], 1.0 op_sel_hi:[1,0]
	v_pk_fma_f32 v[26:27], v[4:5], v[26:27], v[130:131]
	v_pk_fma_f32 v[28:29], v[10:11], v[28:29], v[132:133]
	v_cvt_pk_bf16_f32 v12, v26, v27
	v_cvt_pk_bf16_f32 v13, v28, v29
	global_store_dwordx2 v[92:93], v[12:13], off offset:512
	v_pk_mul_f32 v[22:23], v[102:103], v[22:23]
	v_pk_mul_f32 v[24:25], v[104:105], v[24:25]
	v_pk_add_f32 v[4:5], v[166:167], 1.0 op_sel_hi:[1,0]
	v_pk_add_f32 v[10:11], v[168:169], 1.0 op_sel_hi:[1,0]
	v_pk_fma_f32 v[22:23], v[4:5], v[22:23], v[134:135]
	v_pk_fma_f32 v[24:25], v[10:11], v[24:25], v[136:137]
	v_cvt_pk_bf16_f32 v12, v22, v23
	v_cvt_pk_bf16_f32 v13, v24, v25
	global_store_dwordx2 v[92:93], v[12:13], off offset:1024
	v_pk_mul_f32 v[18:19], v[106:107], v[18:19]
	v_pk_mul_f32 v[20:21], v[108:109], v[20:21]
	v_pk_add_f32 v[4:5], v[170:171], 1.0 op_sel_hi:[1,0]
	v_pk_add_f32 v[10:11], v[172:173], 1.0 op_sel_hi:[1,0]
	v_pk_fma_f32 v[18:19], v[4:5], v[18:19], v[138:139]
	v_pk_fma_f32 v[20:21], v[10:11], v[20:21], v[140:141]
	v_cvt_pk_bf16_f32 v12, v18, v19
	v_cvt_pk_bf16_f32 v13, v20, v21
	global_store_dwordx2 v[92:93], v[12:13], off offset:1536
	v_pk_mul_f32 v[14:15], v[110:111], v[14:15]
	v_pk_mul_f32 v[16:17], v[112:113], v[16:17]
	v_pk_add_f32 v[4:5], v[174:175], 1.0 op_sel_hi:[1,0]
	v_pk_add_f32 v[10:11], v[176:177], 1.0 op_sel_hi:[1,0]
	v_pk_fma_f32 v[14:15], v[4:5], v[14:15], v[142:143]
	v_pk_fma_f32 v[16:17], v[10:11], v[16:17], v[144:145]
	v_cvt_pk_bf16_f32 v12, v14, v15
	v_cvt_pk_bf16_f32 v13, v16, v17
	global_store_dwordx2 v[92:93], v[12:13], off offset:2048
	v_pk_mul_f32 v[6:7], v[114:115], v[6:7]
	v_pk_mul_f32 v[8:9], v[116:117], v[8:9]
	v_pk_add_f32 v[4:5], v[178:179], 1.0 op_sel_hi:[1,0]
	v_pk_add_f32 v[10:11], v[180:181], 1.0 op_sel_hi:[1,0]
	v_pk_fma_f32 v[6:7], v[4:5], v[6:7], v[146:147]
	v_pk_fma_f32 v[8:9], v[10:11], v[8:9], v[148:149]
	v_cvt_pk_bf16_f32 v12, v6, v7
	v_cvt_pk_bf16_f32 v13, v8, v9
	global_store_dwordx2 v[92:93], v[12:13], off offset:2560
	v_pk_mul_f32 v[82:83], v[118:119], v[82:83]
	v_pk_mul_f32 v[84:85], v[120:121], v[84:85]
	v_pk_add_f32 v[4:5], v[182:183], 1.0 op_sel_hi:[1,0]
	v_pk_add_f32 v[10:11], v[184:185], 1.0 op_sel_hi:[1,0]
	v_pk_fma_f32 v[82:83], v[4:5], v[82:83], v[150:151]
	v_pk_fma_f32 v[84:85], v[10:11], v[84:85], v[152:153]
	v_cvt_pk_bf16_f32 v12, v82, v83
	v_cvt_pk_bf16_f32 v13, v84, v85
	global_store_dwordx2 v[92:93], v[12:13], off offset:3072
	v_pk_mul_f32 v[86:87], v[122:123], v[86:87]
	v_pk_mul_f32 v[88:89], v[124:125], v[88:89]
	v_pk_add_f32 v[4:5], v[186:187], 1.0 op_sel_hi:[1,0]
	v_pk_add_f32 v[10:11], v[188:189], 1.0 op_sel_hi:[1,0]
	v_pk_fma_f32 v[86:87], v[4:5], v[86:87], v[154:155]
	v_pk_fma_f32 v[88:89], v[10:11], v[88:89], v[156:157]
	v_cvt_pk_bf16_f32 v12, v86, v87
	v_cvt_pk_bf16_f32 v13, v88, v89
	global_store_dwordx2 v[92:93], v[12:13], off offset:3584
	s_branch .Lnorm_join
.Lnorm_first:
	s_lshl_b32 s83, s32, 13
	s_add_u32 s100, s98, s83
	s_addc_u32 s101, s99, 0
	s_sub_i32 s83, s32, 0x4000
	s_lshl_b32 s83, s83, 13
	s_add_u32 s86, s48, s83
	s_addc_u32 s87, s49, 0
	s_cmp_lt_u32 s32, 0x4000
	s_cselect_b32 s100, s100, s86
	s_cselect_b32 s101, s101, s87
	global_load_dwordx4 v[206:209], v50, s[100:101]
	global_load_dwordx4 v[210:213], v50, s[100:101] offset:1024
	global_load_dwordx4 v[214:217], v50, s[100:101] offset:2048
	global_load_dwordx4 v[218:221], v50, s[100:101] offset:3072
	global_load_dwordx4 v[222:225], v58, s[100:101]
	global_load_dwordx4 v[226:229], v58, s[100:101] offset:1024
	global_load_dwordx4 v[242:245], v58, s[100:101] offset:2048
	global_load_dwordx4 v[246:249], v58, s[100:101] offset:3072
	v_mov_b32_e32 v81, s32
	v_ashrrev_i32_e32 v81, 11, v81
	v_mul_i32_i24_e32 v68, 0x1800, v81
	v_ashrrev_i32_e32 v69, 31, v68
	v_lshl_add_u64 v[68:69], v[68:69], 2, s[6:7]
	v_lshl_add_u64 v[74:75], v[68:69], 0, v[50:51]
	v_lshl_add_u64 v[70:71], v[68:69], 0, s[22:23]
	v_lshl_add_u64 v[90:91], v[70:71], 0, v[50:51]
	v_lshl_add_u64 v[4:5], v[68:69], 0, v[58:59]
	v_lshl_add_u64 v[10:11], v[70:71], 0, v[58:59]
	v_lshl_add_u64 v[92:93], v[46:47], 0, v[72:73]
	global_load_dwordx4 v[94:97], v[36:37], off
	global_load_dwordx4 v[126:129], v[74:75], off
	global_load_dwordx4 v[158:161], v[90:91], off
	global_load_dwordx4 v[98:101], v[36:37], off offset:1024
	global_load_dwordx4 v[130:133], v[74:75], off offset:1024
	global_load_dwordx4 v[162:165], v[90:91], off offset:1024
	global_load_dwordx4 v[102:105], v[36:37], off offset:2048
	global_load_dwordx4 v[134:137], v[74:75], off offset:2048
	global_load_dwordx4 v[166:169], v[90:91], off offset:2048
	global_load_dwordx4 v[106:109], v[36:37], off offset:3072
	global_load_dwordx4 v[138:141], v[74:75], off offset:3072
	global_load_dwordx4 v[170:173], v[90:91], off offset:3072
	global_load_dwordx4 v[110:113], v[38:39], off
	global_load_dwordx4 v[142:145], v[4:5], off
	global_load_dwordx4 v[174:177], v[10:11], off
	global_load_dwordx4 v[114:117], v[38:39], off offset:1024
	global_load_dwordx4 v[146:149], v[4:5], off offset:1024
	global_load_dwordx4 v[178:181], v[10:11], off offset:1024
	global_load_dwordx4 v[118:121], v[38:39], off offset:2048
	global_load_dwordx4 v[150:153], v[4:5], off offset:2048
	global_load_dwordx4 v[182:185], v[10:11], off offset:2048
	global_load_dwordx4 v[122:125], v[38:39], off offset:3072
	global_load_dwordx4 v[154:157], v[4:5], off offset:3072
	global_load_dwordx4 v[186:189], v[10:11], off offset:3072
	s_lshl_b32 s83, s35, 13
	s_add_u32 s100, s98, s83
	s_addc_u32 s101, s99, 0
	s_sub_i32 s83, s35, 0x4000
	s_lshl_b32 s83, s83, 13
	s_add_u32 s86, s48, s83
	s_addc_u32 s87, s49, 0
	s_cmp_lt_u32 s35, 0x4000
	s_cselect_b32 s100, s100, s86
	s_cselect_b32 s101, s101, s87
	s_waitcnt vmcnt(24)
	v_mov_b64_e32 v[30:31], v[206:207]
	v_mov_b64_e32 v[32:33], v[208:209]
	v_mov_b64_e32 v[26:27], v[210:211]
	v_mov_b64_e32 v[28:29], v[212:213]
	v_mov_b64_e32 v[22:23], v[214:215]
	v_mov_b64_e32 v[24:25], v[216:217]
	v_mov_b64_e32 v[18:19], v[218:219]
	v_mov_b64_e32 v[20:21], v[220:221]
	v_mov_b64_e32 v[14:15], v[222:223]
	v_mov_b64_e32 v[16:17], v[224:225]
	v_mov_b64_e32 v[6:7], v[226:227]
	v_mov_b64_e32 v[8:9], v[228:229]
	v_mov_b64_e32 v[82:83], v[242:243]
	v_mov_b64_e32 v[84:85], v[244:245]
	v_mov_b64_e32 v[86:87], v[246:247]
	v_mov_b64_e32 v[88:89], v[248:249]
	global_load_dwordx4 v[206:209], v50, s[100:101]
	global_load_dwordx4 v[210:213], v50, s[100:101] offset:1024
	global_load_dwordx4 v[214:217], v50, s[100:101] offset:2048
	global_load_dwordx4 v[218:221], v50, s[100:101] offset:3072
	global_load_dwordx4 v[222:225], v58, s[100:101]
	global_load_dwordx4 v[226:229], v58, s[100:101] offset:1024
	global_load_dwordx4 v[242:245], v58, s[100:101] offset:2048
	global_load_dwordx4 v[246:249], v58, s[100:101] offset:3072
	v_mov_b32_e32 v34, s35
	v_mov_b32_e32 v35, 0
	v_cmp_lt_i32_e32 vcc, s12, v34
	s_or_b64 s[8:9], vcc, s[8:9]
	v_mul_f32_e32 v4, v31, v31
	v_mul_f32_e32 v5, v27, v27
	v_fmac_f32_e32 v4, v30, v30
	v_fmac_f32_e32 v5, v26, v26
	v_fmac_f32_e32 v4, v32, v32
	v_fmac_f32_e32 v5, v28, v28
	v_fmac_f32_e32 v4, v33, v33
	v_fmac_f32_e32 v5, v29, v29
	v_add_f32_e32 v4, v4, v5
	v_mul_f32_e32 v5, v23, v23
	v_fmac_f32_e32 v5, v22, v22
	v_fmac_f32_e32 v5, v24, v24
	v_fmac_f32_e32 v5, v25, v25
	v_add_f32_e32 v4, v4, v5
	v_mul_f32_e32 v5, v19, v19
	v_fmac_f32_e32 v5, v18, v18
	v_fmac_f32_e32 v5, v20, v20
	v_fmac_f32_e32 v5, v21, v21
	v_mov_b32_e32 v10, v15
	v_mov_b32_e32 v11, v7
	v_add_f32_e32 v12, v4, v5
	v_mov_b32_e32 v4, v14
	v_mov_b32_e32 v5, v6
	v_pk_mul_f32 v[10:11], v[10:11], v[10:11]
	s_nop 0
	v_pk_fma_f32 v[4:5], v[4:5], v[4:5], v[10:11]
	v_mov_b32_e32 v10, v16
	v_mov_b32_e32 v11, v8
	v_pk_fma_f32 v[4:5], v[10:11], v[10:11], v[4:5]
	v_mov_b32_e32 v10, v17
	v_mov_b32_e32 v11, v9
	v_pk_fma_f32 v[4:5], v[10:11], v[10:11], v[4:5]
	s_nop 0
	v_add_f32_e32 v4, v12, v4
	v_add_f32_e32 v66, v4, v5
	v_mov_b32_e32 v74, v83
	v_mov_b32_e32 v75, v87
	v_mov_b32_e32 v70, v82
	v_mov_b32_e32 v71, v86
	v_pk_mul_f32 v[74:75], v[74:75], v[74:75]
	s_nop 0
	v_pk_fma_f32 v[70:71], v[70:71], v[70:71], v[74:75]
	v_mov_b32_e32 v74, v84
	v_mov_b32_e32 v75, v88
	v_pk_fma_f32 v[70:71], v[74:75], v[74:75], v[70:71]
	v_mov_b32_e32 v74, v85
	v_mov_b32_e32 v75, v89
	v_pk_fma_f32 v[70:71], v[74:75], v[74:75], v[70:71]
	s_nop 0
	v_add_f32_e32 v66, v66, v70
	v_add_f32_e32 v66, v66, v71
	ds_bpermute_b32 v70, v67, v66
	s_waitcnt lgkmcnt(0)
	v_add_f32_e32 v66, v66, v70
	ds_bpermute_b32 v70, v76, v66
	s_waitcnt lgkmcnt(0)
	v_add_f32_e32 v66, v66, v70
	ds_bpermute_b32 v70, v77, v66
	s_waitcnt lgkmcnt(0)
	v_add_f32_e32 v66, v66, v70
	ds_bpermute_b32 v70, v78, v66
	s_waitcnt lgkmcnt(0)
	v_add_f32_e32 v66, v66, v70
	ds_bpermute_b32 v70, v79, v66
	s_waitcnt lgkmcnt(0)
	v_add_f32_e32 v66, v66, v70
	ds_bpermute_b32 v70, v80, v66
	s_waitcnt lgkmcnt(0)
	v_add_f32_e32 v66, v66, v70
	v_fmamk_f32 v66, v66, 0x3a000000, v230
	v_cmp_gt_f32_e32 vcc, s70, v66
	v_mul_f32_e32 v70, 0x4b800000, v66
	s_nop 0
	v_cndmask_b32_e32 v66, v66, v70, vcc
	v_rsq_f32_e32 v66, v66
	s_nop 0
	v_mul_f32_e32 v70, 0x45800000, v66
	v_cndmask_b32_e32 v66, v66, v70, vcc
	v_pk_mul_f32 v[30:31], v[30:31], v[66:67] op_sel_hi:[1,0]
	v_pk_mul_f32 v[32:33], v[32:33], v[66:67] op_sel_hi:[1,0]
	v_pk_mul_f32 v[26:27], v[26:27], v[66:67] op_sel_hi:[1,0]
	v_pk_mul_f32 v[28:29], v[28:29], v[66:67] op_sel_hi:[1,0]
	v_pk_mul_f32 v[22:23], v[22:23], v[66:67] op_sel_hi:[1,0]
	v_pk_mul_f32 v[24:25], v[24:25], v[66:67] op_sel_hi:[1,0]
	v_pk_mul_f32 v[18:19], v[18:19], v[66:67] op_sel_hi:[1,0]
	v_pk_mul_f32 v[20:21], v[20:21], v[66:67] op_sel_hi:[1,0]
	v_pk_mul_f32 v[14:15], v[14:15], v[66:67] op_sel_hi:[1,0]
	v_pk_mul_f32 v[16:17], v[16:17], v[66:67] op_sel_hi:[1,0]
	v_pk_mul_f32 v[6:7], v[6:7], v[66:67] op_sel_hi:[1,0]
	v_pk_mul_f32 v[8:9], v[8:9], v[66:67] op_sel_hi:[1,0]
	v_pk_mul_f32 v[82:83], v[82:83], v[66:67] op_sel_hi:[1,0]
	v_pk_mul_f32 v[84:85], v[84:85], v[66:67] op_sel_hi:[1,0]
	v_pk_mul_f32 v[86:87], v[86:87], v[66:67] op_sel_hi:[1,0]
	v_pk_mul_f32 v[88:89], v[88:89], v[66:67] op_sel_hi:[1,0]
	s_waitcnt vmcnt(29)
	v_pk_mul_f32 v[30:31], v[94:95], v[30:31]
	v_pk_mul_f32 v[32:33], v[96:97], v[32:33]
	v_pk_add_f32 v[4:5], v[158:159], 1.0 op_sel_hi:[1,0]
	v_pk_add_f32 v[10:11], v[160:161], 1.0 op_sel_hi:[1,0]
	v_pk_fma_f32 v[30:31], v[4:5], v[30:31], v[126:127]
	v_pk_fma_f32 v[32:33], v[10:11], v[32:33], v[128:129]
	v_cvt_pk_bf16_f32 v12, v30, v31
	v_cvt_pk_bf16_f32 v13, v32, v33
	global_store_dwordx2 v[92:93], v[12:13], off
	s_waitcnt vmcnt(27)
	v_pk_mul_f32 v[26:27], v[98:99], v[26:27]
	v_pk_mul_f32 v[28:29], v[100:101], v[28:29]
	v_pk_add_f32 v[4:5], v[162:163], 1.0 op_sel_hi:[1,0]
	v_pk_add_f32 v[10:11], v[164:165], 1.0 op_sel_hi:[1,0]
	v_pk_fma_f32 v[26:27], v[4:5], v[26:27], v[130:131]
	v_pk_fma_f32 v[28:29], v[10:11], v[28:29], v[132:133]
	v_cvt_pk_bf16_f32 v12, v26, v27
	v_cvt_pk_bf16_f32 v13, v28, v29
	global_store_dwordx2 v[92:93], v[12:13], off offset:512
	s_waitcnt vmcnt(25)
	v_pk_mul_f32 v[22:23], v[102:103], v[22:23]
	v_pk_mul_f32 v[24:25], v[104:105], v[24:25]
	v_pk_add_f32 v[4:5], v[166:167], 1.0 op_sel_hi:[1,0]
	v_pk_add_f32 v[10:11], v[168:169], 1.0 op_sel_hi:[1,0]
	v_pk_fma_f32 v[22:23], v[4:5], v[22:23], v[134:135]
	v_pk_fma_f32 v[24:25], v[10:11], v[24:25], v[136:137]
	v_cvt_pk_bf16_f32 v12, v22, v23
	v_cvt_pk_bf16_f32 v13, v24, v25
	global_store_dwordx2 v[92:93], v[12:13], off offset:1024
	s_waitcnt vmcnt(23)
	v_pk_mul_f32 v[18:19], v[106:107], v[18:19]
	v_pk_mul_f32 v[20:21], v[108:109], v[20:21]
	v_pk_add_f32 v[4:5], v[170:171], 1.0 op_sel_hi:[1,0]
	v_pk_add_f32 v[10:11], v[172:173], 1.0 op_sel_hi:[1,0]
	v_pk_fma_f32 v[18:19], v[4:5], v[18:19], v[138:139]
	v_pk_fma_f32 v[20:21], v[10:11], v[20:21], v[140:141]
	v_cvt_pk_bf16_f32 v12, v18, v19
	v_cvt_pk_bf16_f32 v13, v20, v21
	global_store_dwordx2 v[92:93], v[12:13], off offset:1536
	s_waitcnt vmcnt(21)
	v_pk_mul_f32 v[14:15], v[110:111], v[14:15]
	v_pk_mul_f32 v[16:17], v[112:113], v[16:17]
	v_pk_add_f32 v[4:5], v[174:175], 1.0 op_sel_hi:[1,0]
	v_pk_add_f32 v[10:11], v[176:177], 1.0 op_sel_hi:[1,0]
	v_pk_fma_f32 v[14:15], v[4:5], v[14:15], v[142:143]
	v_pk_fma_f32 v[16:17], v[10:11], v[16:17], v[144:145]
	v_cvt_pk_bf16_f32 v12, v14, v15
	v_cvt_pk_bf16_f32 v13, v16, v17
	global_store_dwordx2 v[92:93], v[12:13], off offset:2048
	s_waitcnt vmcnt(19)
	v_pk_mul_f32 v[6:7], v[114:115], v[6:7]
	v_pk_mul_f32 v[8:9], v[116:117], v[8:9]
	v_pk_add_f32 v[4:5], v[178:179], 1.0 op_sel_hi:[1,0]
	v_pk_add_f32 v[10:11], v[180:181], 1.0 op_sel_hi:[1,0]
	v_pk_fma_f32 v[6:7], v[4:5], v[6:7], v[146:147]
	v_pk_fma_f32 v[8:9], v[10:11], v[8:9], v[148:149]
	v_cvt_pk_bf16_f32 v12, v6, v7
	v_cvt_pk_bf16_f32 v13, v8, v9
	global_store_dwordx2 v[92:93], v[12:13], off offset:2560
	s_waitcnt vmcnt(17)
	v_pk_mul_f32 v[82:83], v[118:119], v[82:83]
	v_pk_mul_f32 v[84:85], v[120:121], v[84:85]
	v_pk_add_f32 v[4:5], v[182:183], 1.0 op_sel_hi:[1,0]
	v_pk_add_f32 v[10:11], v[184:185], 1.0 op_sel_hi:[1,0]
	v_pk_fma_f32 v[82:83], v[4:5], v[82:83], v[150:151]
	v_pk_fma_f32 v[84:85], v[10:11], v[84:85], v[152:153]
	v_cvt_pk_bf16_f32 v12, v82, v83
	v_cvt_pk_bf16_f32 v13, v84, v85
	global_store_dwordx2 v[92:93], v[12:13], off offset:3072
	s_waitcnt vmcnt(15)
	v_pk_mul_f32 v[86:87], v[122:123], v[86:87]
	v_pk_mul_f32 v[88:89], v[124:125], v[88:89]
	v_pk_add_f32 v[4:5], v[186:187], 1.0 op_sel_hi:[1,0]
	v_pk_add_f32 v[10:11], v[188:189], 1.0 op_sel_hi:[1,0]
	v_pk_fma_f32 v[86:87], v[4:5], v[86:87], v[154:155]
	v_pk_fma_f32 v[88:89], v[10:11], v[88:89], v[156:157]
	v_cvt_pk_bf16_f32 v12, v86, v87
	v_cvt_pk_bf16_f32 v13, v88, v89
	global_store_dwordx2 v[92:93], v[12:13], off offset:3584
	s_branch .Lnorm_join
.Lnorm_ctx:
	v_mov_b32_e32 v81, 8
	v_mul_i32_i24_e32 v68, 0x1800, v81
	v_ashrrev_i32_e32 v69, 31, v68
	v_lshl_add_u64 v[68:69], v[68:69], 2, s[6:7]
	v_lshl_add_u64 v[74:75], v[68:69], 0, v[50:51]
	v_lshl_add_u64 v[70:71], v[68:69], 0, s[22:23]
	v_lshl_add_u64 v[90:91], v[70:71], 0, v[50:51]
	v_lshl_add_u64 v[4:5], v[68:69], 0, v[58:59]
	v_lshl_add_u64 v[10:11], v[70:71], 0, v[58:59]
	v_lshl_add_u64 v[92:93], v[46:47], 0, v[72:73]
	global_load_dwordx4 v[94:97], v[36:37], off
	global_load_dwordx4 v[126:129], v[74:75], off
	global_load_dwordx4 v[158:161], v[90:91], off
	global_load_dwordx4 v[98:101], v[36:37], off offset:1024
	global_load_dwordx4 v[130:133], v[74:75], off offset:1024
	global_load_dwordx4 v[162:165], v[90:91], off offset:1024
	global_load_dwordx4 v[102:105], v[36:37], off offset:2048
	global_load_dwordx4 v[134:137], v[74:75], off offset:2048
	global_load_dwordx4 v[166:169], v[90:91], off offset:2048
	global_load_dwordx4 v[106:109], v[36:37], off offset:3072
	global_load_dwordx4 v[138:141], v[74:75], off offset:3072
	global_load_dwordx4 v[170:173], v[90:91], off offset:3072
	global_load_dwordx4 v[110:113], v[38:39], off
	global_load_dwordx4 v[142:145], v[4:5], off
	global_load_dwordx4 v[174:177], v[10:11], off
	global_load_dwordx4 v[114:117], v[38:39], off offset:1024
	global_load_dwordx4 v[146:149], v[4:5], off offset:1024
	global_load_dwordx4 v[178:181], v[10:11], off offset:1024
	global_load_dwordx4 v[118:121], v[38:39], off offset:2048
	global_load_dwordx4 v[150:153], v[4:5], off offset:2048
	global_load_dwordx4 v[182:185], v[10:11], off offset:2048
	global_load_dwordx4 v[122:125], v[38:39], off offset:3072
	global_load_dwordx4 v[154:157], v[4:5], off offset:3072
	global_load_dwordx4 v[186:189], v[10:11], off offset:3072
	s_waitcnt vmcnt(32)
	v_mov_b64_e32 v[30:31], v[206:207]
	v_mov_b64_e32 v[32:33], v[208:209]
	v_mov_b64_e32 v[26:27], v[210:211]
	v_mov_b64_e32 v[28:29], v[212:213]
	v_mov_b64_e32 v[22:23], v[214:215]
	v_mov_b64_e32 v[24:25], v[216:217]
	v_mov_b64_e32 v[18:19], v[218:219]
	v_mov_b64_e32 v[20:21], v[220:221]
	v_mov_b64_e32 v[14:15], v[222:223]
	v_mov_b64_e32 v[16:17], v[224:225]
	v_mov_b64_e32 v[6:7], v[226:227]
	v_mov_b64_e32 v[8:9], v[228:229]
	v_mov_b64_e32 v[82:83], v[242:243]
	v_mov_b64_e32 v[84:85], v[244:245]
	v_mov_b64_e32 v[86:87], v[246:247]
	v_mov_b64_e32 v[88:89], v[248:249]
	v_mov_b32_e32 v34, s35
	v_mov_b32_e32 v35, 0
	v_cmp_lt_i32_e32 vcc, s12, v34
	s_or_b64 s[8:9], vcc, s[8:9]
	v_mul_f32_e32 v4, v31, v31
	v_mul_f32_e32 v5, v27, v27
	v_fmac_f32_e32 v4, v30, v30
	v_fmac_f32_e32 v5, v26, v26
	v_fmac_f32_e32 v4, v32, v32
	v_fmac_f32_e32 v5, v28, v28
	v_fmac_f32_e32 v4, v33, v33
	v_fmac_f32_e32 v5, v29, v29
	v_add_f32_e32 v4, v4, v5
	v_mul_f32_e32 v5, v23, v23
	v_fmac_f32_e32 v5, v22, v22
	v_fmac_f32_e32 v5, v24, v24
	v_fmac_f32_e32 v5, v25, v25
	v_add_f32_e32 v4, v4, v5
	v_mul_f32_e32 v5, v19, v19
	v_fmac_f32_e32 v5, v18, v18
	v_fmac_f32_e32 v5, v20, v20
	v_fmac_f32_e32 v5, v21, v21
	v_mov_b32_e32 v10, v15
	v_mov_b32_e32 v11, v7
	v_add_f32_e32 v12, v4, v5
	v_mov_b32_e32 v4, v14
	v_mov_b32_e32 v5, v6
	v_pk_mul_f32 v[10:11], v[10:11], v[10:11]
	s_nop 0
	v_pk_fma_f32 v[4:5], v[4:5], v[4:5], v[10:11]
	v_mov_b32_e32 v10, v16
	v_mov_b32_e32 v11, v8
	v_pk_fma_f32 v[4:5], v[10:11], v[10:11], v[4:5]
	v_mov_b32_e32 v10, v17
	v_mov_b32_e32 v11, v9
	v_pk_fma_f32 v[4:5], v[10:11], v[10:11], v[4:5]
	s_nop 0
	v_add_f32_e32 v4, v12, v4
	v_add_f32_e32 v66, v4, v5
	v_mov_b32_e32 v74, v83
	v_mov_b32_e32 v75, v87
	v_mov_b32_e32 v70, v82
	v_mov_b32_e32 v71, v86
	v_pk_mul_f32 v[74:75], v[74:75], v[74:75]
	s_nop 0
	v_pk_fma_f32 v[70:71], v[70:71], v[70:71], v[74:75]
	v_mov_b32_e32 v74, v84
	v_mov_b32_e32 v75, v88
	v_pk_fma_f32 v[70:71], v[74:75], v[74:75], v[70:71]
	v_mov_b32_e32 v74, v85
	v_mov_b32_e32 v75, v89
	v_pk_fma_f32 v[70:71], v[74:75], v[74:75], v[70:71]
	s_nop 0
	v_add_f32_e32 v66, v66, v70
	v_add_f32_e32 v66, v66, v71
	ds_bpermute_b32 v70, v67, v66
	s_waitcnt lgkmcnt(0)
	v_add_f32_e32 v66, v66, v70
	ds_bpermute_b32 v70, v76, v66
	s_waitcnt lgkmcnt(0)
	v_add_f32_e32 v66, v66, v70
	ds_bpermute_b32 v70, v77, v66
	s_waitcnt lgkmcnt(0)
	v_add_f32_e32 v66, v66, v70
	ds_bpermute_b32 v70, v78, v66
	s_waitcnt lgkmcnt(0)
	v_add_f32_e32 v66, v66, v70
	ds_bpermute_b32 v70, v79, v66
	s_waitcnt lgkmcnt(0)
	v_add_f32_e32 v66, v66, v70
	ds_bpermute_b32 v70, v80, v66
	s_waitcnt lgkmcnt(0)
	v_add_f32_e32 v66, v66, v70
	v_fmamk_f32 v66, v66, 0x3a000000, v230
	v_cmp_gt_f32_e32 vcc, s70, v66
	v_mul_f32_e32 v70, 0x4b800000, v66
	s_nop 0
	v_cndmask_b32_e32 v66, v66, v70, vcc
	v_rsq_f32_e32 v66, v66
	s_nop 0
	v_mul_f32_e32 v70, 0x45800000, v66
	v_cndmask_b32_e32 v66, v66, v70, vcc
	v_pk_mul_f32 v[30:31], v[30:31], v[66:67] op_sel_hi:[1,0]
	v_pk_mul_f32 v[32:33], v[32:33], v[66:67] op_sel_hi:[1,0]
	v_pk_mul_f32 v[26:27], v[26:27], v[66:67] op_sel_hi:[1,0]
	v_pk_mul_f32 v[28:29], v[28:29], v[66:67] op_sel_hi:[1,0]
	v_pk_mul_f32 v[22:23], v[22:23], v[66:67] op_sel_hi:[1,0]
	v_pk_mul_f32 v[24:25], v[24:25], v[66:67] op_sel_hi:[1,0]
	v_pk_mul_f32 v[18:19], v[18:19], v[66:67] op_sel_hi:[1,0]
	v_pk_mul_f32 v[20:21], v[20:21], v[66:67] op_sel_hi:[1,0]
	v_pk_mul_f32 v[14:15], v[14:15], v[66:67] op_sel_hi:[1,0]
	v_pk_mul_f32 v[16:17], v[16:17], v[66:67] op_sel_hi:[1,0]
	v_pk_mul_f32 v[6:7], v[6:7], v[66:67] op_sel_hi:[1,0]
	v_pk_mul_f32 v[8:9], v[8:9], v[66:67] op_sel_hi:[1,0]
	v_pk_mul_f32 v[82:83], v[82:83], v[66:67] op_sel_hi:[1,0]
	v_pk_mul_f32 v[84:85], v[84:85], v[66:67] op_sel_hi:[1,0]
	v_pk_mul_f32 v[86:87], v[86:87], v[66:67] op_sel_hi:[1,0]
	v_pk_mul_f32 v[88:89], v[88:89], v[66:67] op_sel_hi:[1,0]
	s_waitcnt vmcnt(21)
	v_pk_mul_f32 v[30:31], v[94:95], v[30:31]
	v_pk_mul_f32 v[32:33], v[96:97], v[32:33]
	v_pk_add_f32 v[4:5], v[158:159], 1.0 op_sel_hi:[1,0]
	v_pk_add_f32 v[10:11], v[160:161], 1.0 op_sel_hi:[1,0]
	v_pk_fma_f32 v[30:31], v[4:5], v[30:31], v[126:127]
	v_pk_fma_f32 v[32:33], v[10:11], v[32:33], v[128:129]
	v_cvt_pk_bf16_f32 v12, v30, v31
	v_cvt_pk_bf16_f32 v13, v32, v33
	global_store_dwordx2 v[92:93], v[12:13], off
	s_waitcnt vmcnt(19)
	v_pk_mul_f32 v[26:27], v[98:99], v[26:27]
	v_pk_mul_f32 v[28:29], v[100:101], v[28:29]
	v_pk_add_f32 v[4:5], v[162:163], 1.0 op_sel_hi:[1,0]
	v_pk_add_f32 v[10:11], v[164:165], 1.0 op_sel_hi:[1,0]
	v_pk_fma_f32 v[26:27], v[4:5], v[26:27], v[130:131]
	v_pk_fma_f32 v[28:29], v[10:11], v[28:29], v[132:133]
	v_cvt_pk_bf16_f32 v12, v26, v27
	v_cvt_pk_bf16_f32 v13, v28, v29
	global_store_dwordx2 v[92:93], v[12:13], off offset:512
	s_waitcnt vmcnt(17)
	v_pk_mul_f32 v[22:23], v[102:103], v[22:23]
	v_pk_mul_f32 v[24:25], v[104:105], v[24:25]
	v_pk_add_f32 v[4:5], v[166:167], 1.0 op_sel_hi:[1,0]
	v_pk_add_f32 v[10:11], v[168:169], 1.0 op_sel_hi:[1,0]
	v_pk_fma_f32 v[22:23], v[4:5], v[22:23], v[134:135]
	v_pk_fma_f32 v[24:25], v[10:11], v[24:25], v[136:137]
	v_cvt_pk_bf16_f32 v12, v22, v23
	v_cvt_pk_bf16_f32 v13, v24, v25
	global_store_dwordx2 v[92:93], v[12:13], off offset:1024
	s_waitcnt vmcnt(15)
	v_pk_mul_f32 v[18:19], v[106:107], v[18:19]
	v_pk_mul_f32 v[20:21], v[108:109], v[20:21]
	v_pk_add_f32 v[4:5], v[170:171], 1.0 op_sel_hi:[1,0]
	v_pk_add_f32 v[10:11], v[172:173], 1.0 op_sel_hi:[1,0]
	v_pk_fma_f32 v[18:19], v[4:5], v[18:19], v[138:139]
	v_pk_fma_f32 v[20:21], v[10:11], v[20:21], v[140:141]
	v_cvt_pk_bf16_f32 v12, v18, v19
	v_cvt_pk_bf16_f32 v13, v20, v21
	global_store_dwordx2 v[92:93], v[12:13], off offset:1536
	s_waitcnt vmcnt(13)
	v_pk_mul_f32 v[14:15], v[110:111], v[14:15]
	v_pk_mul_f32 v[16:17], v[112:113], v[16:17]
	v_pk_add_f32 v[4:5], v[174:175], 1.0 op_sel_hi:[1,0]
	v_pk_add_f32 v[10:11], v[176:177], 1.0 op_sel_hi:[1,0]
	v_pk_fma_f32 v[14:15], v[4:5], v[14:15], v[142:143]
	v_pk_fma_f32 v[16:17], v[10:11], v[16:17], v[144:145]
	v_cvt_pk_bf16_f32 v12, v14, v15
	v_cvt_pk_bf16_f32 v13, v16, v17
	global_store_dwordx2 v[92:93], v[12:13], off offset:2048
	s_waitcnt vmcnt(11)
	v_pk_mul_f32 v[6:7], v[114:115], v[6:7]
	v_pk_mul_f32 v[8:9], v[116:117], v[8:9]
	v_pk_add_f32 v[4:5], v[178:179], 1.0 op_sel_hi:[1,0]
	v_pk_add_f32 v[10:11], v[180:181], 1.0 op_sel_hi:[1,0]
	v_pk_fma_f32 v[6:7], v[4:5], v[6:7], v[146:147]
	v_pk_fma_f32 v[8:9], v[10:11], v[8:9], v[148:149]
	v_cvt_pk_bf16_f32 v12, v6, v7
	v_cvt_pk_bf16_f32 v13, v8, v9
	global_store_dwordx2 v[92:93], v[12:13], off offset:2560
	s_waitcnt vmcnt(9)
	v_pk_mul_f32 v[82:83], v[118:119], v[82:83]
	v_pk_mul_f32 v[84:85], v[120:121], v[84:85]
	v_pk_add_f32 v[4:5], v[182:183], 1.0 op_sel_hi:[1,0]
	v_pk_add_f32 v[10:11], v[184:185], 1.0 op_sel_hi:[1,0]
	v_pk_fma_f32 v[82:83], v[4:5], v[82:83], v[150:151]
	v_pk_fma_f32 v[84:85], v[10:11], v[84:85], v[152:153]
	v_cvt_pk_bf16_f32 v12, v82, v83
	v_cvt_pk_bf16_f32 v13, v84, v85
	global_store_dwordx2 v[92:93], v[12:13], off offset:3072
	s_waitcnt vmcnt(7)
	v_pk_mul_f32 v[86:87], v[122:123], v[86:87]
	v_pk_mul_f32 v[88:89], v[124:125], v[88:89]
	v_pk_add_f32 v[4:5], v[186:187], 1.0 op_sel_hi:[1,0]
	v_pk_add_f32 v[10:11], v[188:189], 1.0 op_sel_hi:[1,0]
	v_pk_fma_f32 v[86:87], v[4:5], v[86:87], v[154:155]
	v_pk_fma_f32 v[88:89], v[10:11], v[88:89], v[156:157]
	v_cvt_pk_bf16_f32 v12, v86, v87
	v_cvt_pk_bf16_f32 v13, v88, v89
	global_store_dwordx2 v[92:93], v[12:13], off offset:3584
